# grid barrier: cache invalidate issued at arrival (overlaps the wait) instead of after the release is seen
# speedup vs baseline: 1.0343x; 1.0015x over previous
.LBB0_101:
	s_mov_b64 s[8:9], exec
	s_lshl_b32 s6, s33, 8
	v_mbcnt_lo_u32_b32 v1, s8, 0
	s_add_u32 s6, s40, s6
	v_mbcnt_hi_u32_b32 v1, s9, v1
	s_addc_u32 s7, s41, 0
	v_cmp_eq_u32_e32 vcc, 0, v1
	s_and_saveexec_b64 s[10:11], vcc
	s_cbranch_execz .LBB0_103
	s_bcnt1_i32_b64 s8, s[8:9]
	v_mov_b32_e32 v3, 0x1000
	v_mov_b32_e32 v4, s8
	global_atomic_add v3, v3, v4, s[6:7] offset:1024 sc0
	buffer_inv sc1

.LBB0_116:
	s_or_b64 exec, exec, s[10:11]
	s_waitcnt vmcnt(0)
	s_nop 0
	s_waitcnt vmcnt(0)

.LBB0_134:
	s_or_b64 exec, exec, s[8:9]
	s_mov_b64 s[8:9], exec
	v_mbcnt_lo_u32_b32 v0, s8, 0
	v_mbcnt_hi_u32_b32 v0, s9, v0
	v_cmp_eq_u32_e32 vcc, 0, v0
	s_waitcnt vmcnt(0)
	s_nop 0
	s_and_saveexec_b64 s[10:11], vcc
	s_cbranch_execz .LBB0_136
	s_bcnt1_i32_b64 s8, s[8:9]
	v_mov_b32_e32 v0, 0x2000
	v_mov_b32_e32 v1, s8
	s_nop 0

.LBB0_217:
	s_mov_b64 s[12:13], exec
	s_lshl_b32 s6, s33, 8
	v_mbcnt_lo_u32_b32 v1, s12, 0
	s_add_u32 s8, s40, s6
	v_mbcnt_hi_u32_b32 v1, s13, v1
	s_addc_u32 s9, s41, 0
	v_cmp_eq_u32_e32 vcc, 0, v1
	s_and_saveexec_b64 s[14:15], vcc
	s_cbranch_execz .LBB0_219
	s_bcnt1_i32_b64 s6, s[12:13]
	v_mov_b32_e32 v3, 0x1000
	v_mov_b32_e32 v4, s6
	global_atomic_add v3, v3, v4, s[8:9] offset:1024 sc0
	buffer_inv sc1

.LBB0_232:
	s_or_b64 exec, exec, s[14:15]
	s_waitcnt vmcnt(0)
	s_nop 0
	s_waitcnt vmcnt(0)

.LBB0_250:
	s_or_b64 exec, exec, s[12:13]
	s_mov_b64 s[12:13], exec
	v_mbcnt_lo_u32_b32 v0, s12, 0
	v_mbcnt_hi_u32_b32 v0, s13, v0
	v_cmp_eq_u32_e32 vcc, 0, v0
	s_waitcnt vmcnt(0)
	s_nop 0
	s_and_saveexec_b64 s[14:15], vcc
	s_cbranch_execz .LBB0_252
	s_bcnt1_i32_b64 s6, s[12:13]
	v_mov_b32_e32 v0, 0x2000
	v_mov_b32_e32 v1, s6
	s_nop 0

.LBB0_282:
	s_mov_b64 s[12:13], exec
	s_lshl_b32 s8, s33, 8
	v_mbcnt_lo_u32_b32 v1, s12, 0
	s_add_u32 s8, s40, s8
	v_mbcnt_hi_u32_b32 v1, s13, v1
	s_addc_u32 s9, s41, 0
	v_cmp_eq_u32_e32 vcc, 0, v1
	s_and_saveexec_b64 s[14:15], vcc
	s_cbranch_execz .LBB0_284
	s_bcnt1_i32_b64 s12, s[12:13]
	v_mov_b32_e32 v3, 0x1000
	v_mov_b32_e32 v4, s12
	global_atomic_add v3, v3, v4, s[8:9] offset:1024 sc0
	buffer_inv sc1

.LBB0_315:
	s_or_b64 exec, exec, s[12:13]
	s_mov_b64 s[12:13], exec
	v_mbcnt_lo_u32_b32 v0, s12, 0
	v_mbcnt_hi_u32_b32 v0, s13, v0
	v_cmp_eq_u32_e32 vcc, 0, v0
	s_waitcnt vmcnt(0)
	s_nop 0
	s_and_saveexec_b64 s[14:15], vcc
	s_cbranch_execz .LBB0_317
	s_bcnt1_i32_b64 s12, s[12:13]
	v_mov_b32_e32 v0, 0x2000
	v_mov_b32_e32 v1, s12
	s_nop 0

.LBB0_376:
	s_mov_b64 s[12:13], exec
	s_lshl_b32 s10, s33, 8
	v_mbcnt_lo_u32_b32 v1, s12, 0
	s_add_u32 s10, s40, s10
	v_mbcnt_hi_u32_b32 v1, s13, v1
	s_addc_u32 s11, s41, 0
	v_cmp_eq_u32_e32 vcc, 0, v1
	s_and_saveexec_b64 s[14:15], vcc
	s_cbranch_execz .LBB0_378
	s_bcnt1_i32_b64 s12, s[12:13]
	v_mov_b32_e32 v3, 0x1000
	v_mov_b32_e32 v4, s12
	global_atomic_add v3, v3, v4, s[10:11] offset:1024 sc0
	buffer_inv sc1

.LBB0_463:
	s_mov_b64 s[12:13], exec
	s_lshl_b32 s6, s33, 8
	v_mbcnt_lo_u32_b32 v1, s12, 0
	s_add_u32 s10, s40, s6
	v_mbcnt_hi_u32_b32 v1, s13, v1
	s_addc_u32 s11, s41, 0
	v_cmp_eq_u32_e32 vcc, 0, v1
	s_and_saveexec_b64 s[14:15], vcc
	s_cbranch_execz .LBB0_465
	s_bcnt1_i32_b64 s6, s[12:13]
	v_mov_b32_e32 v3, 0x1000
	v_mov_b32_e32 v4, s6
	global_atomic_add v3, v3, v4, s[10:11] offset:1024 sc0
	buffer_inv sc1

.LBB0_496:
	s_or_b64 exec, exec, s[14:15]
	s_mov_b64 s[14:15], exec
	v_mbcnt_lo_u32_b32 v0, s14, 0
	v_mbcnt_hi_u32_b32 v0, s15, v0
	v_cmp_eq_u32_e32 vcc, 0, v0
	s_waitcnt vmcnt(0)
	s_nop 0
	s_and_saveexec_b64 s[16:17], vcc
	s_cbranch_execz .LBB0_498
	s_bcnt1_i32_b64 s6, s[14:15]
	v_mov_b32_e32 v0, 0x2000
	v_mov_b32_e32 v1, s6
	s_nop 0

.LBB0_991:
	s_mov_b64 s[10:11], exec
	s_lshl_b32 s8, s33, 8
	v_mbcnt_lo_u32_b32 v1, s10, 0
	s_add_u32 s8, s40, s8
	v_mbcnt_hi_u32_b32 v1, s11, v1
	s_addc_u32 s9, s41, 0
	v_cmp_eq_u32_e32 vcc, 0, v1
	s_and_saveexec_b64 s[12:13], vcc
	s_cbranch_execz .LBB0_993
	s_bcnt1_i32_b64 s10, s[10:11]
	v_mov_b32_e32 v3, 0x1000
	v_mov_b32_e32 v4, s10
	global_atomic_add v3, v3, v4, s[8:9] offset:1024 sc0
	buffer_inv sc1

.LBB0_1006:
	s_or_b64 exec, exec, s[12:13]
	s_waitcnt vmcnt(0)
	s_nop 0
	s_waitcnt vmcnt(0)

.LBB0_1024:
	s_or_b64 exec, exec, s[10:11]
	s_mov_b64 s[10:11], exec
	v_mbcnt_lo_u32_b32 v0, s10, 0
	v_mbcnt_hi_u32_b32 v0, s11, v0
	v_cmp_eq_u32_e32 vcc, 0, v0
	s_waitcnt vmcnt(0)
	s_nop 0
	s_and_saveexec_b64 s[12:13], vcc
	s_cbranch_execz .LBB0_1026
	s_bcnt1_i32_b64 s10, s[10:11]
	v_mov_b32_e32 v0, 0x2000
	v_mov_b32_e32 v1, s10
	s_nop 0

.LBB0_1266:
	s_mov_b64 s[4:5], exec
	s_lshl_b32 s2, s33, 8
	v_mbcnt_lo_u32_b32 v17, s4, 0
	s_add_u32 s2, s40, s2
	v_mbcnt_hi_u32_b32 v17, s5, v17
	s_addc_u32 s3, s41, 0
	v_cmp_eq_u32_e32 vcc, 0, v17
	s_and_saveexec_b64 s[10:11], vcc
	s_cbranch_execz .LBB0_1268
	s_bcnt1_i32_b64 s4, s[4:5]
	v_mov_b32_e32 v19, 0x1000
	v_mov_b32_e32 v20, s4
	global_atomic_add v19, v19, v20, s[2:3] offset:1024 sc0
	buffer_inv sc1

.LBB0_1299:
	s_or_b64 exec, exec, s[4:5]
	s_mov_b64 s[4:5], exec
	v_mbcnt_lo_u32_b32 v16, s4, 0
	v_mbcnt_hi_u32_b32 v16, s5, v16
	v_cmp_eq_u32_e32 vcc, 0, v16
	s_waitcnt vmcnt(0)
	s_nop 0
	s_and_saveexec_b64 s[10:11], vcc
	s_cbranch_execz .LBB0_1301
	s_bcnt1_i32_b64 s4, s[4:5]
	v_mov_b32_e32 v16, 0x2000
	v_mov_b32_e32 v17, s4
	s_nop 0
